# SwiGLU epilogues (P1, P7) rewritten with packed f32 mul/fma: 128 fewer VALU instructions per wave per tile, same per-element operations
# baseline (speedup 1.0000x reference)
; __device__ __forceinline__ unsigned cvt_pk_bf16(float lo, float hi) { unsigned r; asm volatile("v_cvt_pk_bf16_f32 %0, %1, %2" : "=v"(r) : "v"(lo), "v"(hi)); return r; }
;     __device__ __forceinline__ void operator()(f32x4 (&acc)[2][2][4][2], const Unit& u, int wr, int wc, int fr, int fq) const {
;     ...
;             for (int m = 0; m < 4; ++m) sq[ai][m] = ssq[row0 + ai * HALF + m * 16];
; #pragma unroll
;         for (int ai = 0; ai < 2; ++ai)
; #pragma unroll
;             for (int m = 0; m < 4; ++m) { const float ms = sq[ai][m] * (1.0f / 1024.0f) + 1e-6f, nrl = -__builtin_amdgcn_rsqf(ms) * LOG2E;
;                 float o[8];
; #pragma unroll
;                 for (int n = 0; n < 2; ++n)
; #pragma unroll
;                     for (int e = 0; e < 4; ++e) { const float a = acc[ai][0][m][n][e], bb = acc[ai][1][m][n][e];
;                         o[4 * n + e] = (a * bb) * __builtin_amdgcn_rcpf(__builtin_fmaf(__builtin_amdgcn_exp2f(a * nrl), ms, ms)); }
;                 u32x4 w; w.x = cvt_pk_bf16(o[0], o[1]); w.y = cvt_pk_bf16(o[2], o[3]); w.z = cvt_pk_bf16(o[4], o[5]); w.w = cvt_pk_bf16(o[6], o[7]);
;                 *(u32x4*)((char*)Ob + ai * HTB + lds_byte(wr * 64 + m * 16 + fr, (col0 & 63))) = w; }
.LBB0_144:
	v_lshl_add_u32 v150, s68, 8, v142
	v_ashrrev_i32_e32 v151, 31, v150
	v_lshl_add_u64 v[150:151], v[150:151], 2, s[22:23]
	global_load_dword v149, v[150:151], off
	global_load_dword v152, v[150:151], off offset:64
	global_load_dword v156, v[150:151], off offset:128
	global_load_dword v157, v[150:151], off offset:192
	global_load_dword v158, v[150:151], off offset:512
	global_load_dword v159, v[150:151], off offset:576
	global_load_dword v160, v[150:151], off offset:640
	global_load_dword v178, v[150:151], off offset:704
	s_lshl_b32 s8, s69, 7
	s_or_b32 s8, s8, s79
	s_mul_i32 s9, s68, 44
	s_ashr_i32 s8, s8, 6
	s_add_i32 s8, s8, s9
	s_ashr_i32 s9, s8, 31
	s_lshl_b64 s[8:9], s[8:9], 15
	s_add_u32 s68, s28, s8
	s_addc_u32 s69, s29, s9
	v_pk_mul_f32 v[124:125], v[116:117], v[124:125]
	v_pk_mul_f32 v[126:127], v[118:119], v[126:127]
	v_pk_mul_f32 v[120:121], v[112:113], v[120:121]
	v_pk_mul_f32 v[122:123], v[114:115], v[122:123]
	v_pk_mul_f32 v[104:105], v[108:109], v[104:105]
	v_pk_mul_f32 v[106:107], v[110:111], v[106:107]
	v_pk_mul_f32 v[96:97], v[100:101], v[96:97]
	v_pk_mul_f32 v[98:99], v[102:103], v[98:99]
	v_pk_mul_f32 v[88:89], v[92:93], v[88:89]
	v_pk_mul_f32 v[90:91], v[94:95], v[90:91]
	v_pk_mul_f32 v[80:81], v[84:85], v[80:81]
	v_pk_mul_f32 v[82:83], v[86:87], v[82:83]
	v_pk_mul_f32 v[72:73], v[76:77], v[72:73]
	v_pk_mul_f32 v[74:75], v[78:79], v[74:75]
	v_pk_mul_f32 v[64:65], v[68:69], v[64:65]
	v_pk_mul_f32 v[66:67], v[70:71], v[66:67]
	v_pk_mul_f32 v[56:57], v[60:61], v[56:57]
	v_pk_mul_f32 v[58:59], v[62:63], v[58:59]
	v_pk_mul_f32 v[48:49], v[52:53], v[48:49]
	v_pk_mul_f32 v[50:51], v[54:55], v[50:51]
	v_pk_mul_f32 v[40:41], v[44:45], v[40:41]
	v_pk_mul_f32 v[42:43], v[46:47], v[42:43]
	v_pk_mul_f32 v[32:33], v[36:37], v[32:33]
	v_pk_mul_f32 v[34:35], v[38:39], v[34:35]
	v_pk_mul_f32 v[24:25], v[28:29], v[24:25]
	v_pk_mul_f32 v[26:27], v[30:31], v[26:27]
	v_pk_mul_f32 v[16:17], v[20:21], v[16:17]
	v_pk_mul_f32 v[18:19], v[22:23], v[18:19]
	v_pk_mul_f32 v[8:9], v[12:13], v[8:9]
	v_pk_mul_f32 v[10:11], v[14:15], v[10:11]
	v_pk_mul_f32 v[0:1], v[4:5], v[0:1]
	v_pk_mul_f32 v[2:3], v[6:7], v[2:3]
	v_readlane_b32 s99, v246, 6
	s_nop 1
	s_cmp_lt_u32 s99, 4
	s_cbranch_scc0 .Lnoal_0
	s_barrier
.Lnoal_0:
	s_waitcnt vmcnt(0)
	v_fmamk_f32 v154, v149, 0x3a800000, v148
	v_fmamk_f32 v162, v152, 0x3a800000, v148
	v_fmamk_f32 v164, v156, 0x3a800000, v148
	v_fmamk_f32 v166, v157, 0x3a800000, v148
	v_fmamk_f32 v168, v158, 0x3a800000, v148
	v_fmamk_f32 v170, v159, 0x3a800000, v148
	v_fmamk_f32 v172, v160, 0x3a800000, v148
	v_fmamk_f32 v174, v178, 0x3a800000, v148
	v_rsq_f32_e32 v155, v154
	v_rsq_f32_e32 v163, v162
	v_rsq_f32_e32 v165, v164
	v_rsq_f32_e32 v167, v166
	v_rsq_f32_e32 v169, v168
	v_rsq_f32_e32 v171, v170
	v_rsq_f32_e32 v173, v172
	v_rsq_f32_e32 v175, v174
	v_mul_f32_e32 v155, 0xbfb8aa3b, v155
	v_mul_f32_e32 v163, 0xbfb8aa3b, v163
	v_mul_f32_e32 v165, 0xbfb8aa3b, v165
	v_mul_f32_e32 v167, 0xbfb8aa3b, v167
	v_mul_f32_e32 v169, 0xbfb8aa3b, v169
	v_mul_f32_e32 v171, 0xbfb8aa3b, v171
	v_mul_f32_e32 v173, 0xbfb8aa3b, v173
	v_mul_f32_e32 v175, 0xbfb8aa3b, v175
	v_pk_mul_f32 v[116:117], v[116:117], v[154:155] op_sel:[0,1] op_sel_hi:[1,1]
	v_pk_mul_f32 v[118:119], v[118:119], v[154:155] op_sel:[0,1] op_sel_hi:[1,1]
	v_pk_mul_f32 v[112:113], v[112:113], v[154:155] op_sel:[0,1] op_sel_hi:[1,1]
	v_pk_mul_f32 v[114:115], v[114:115], v[154:155] op_sel:[0,1] op_sel_hi:[1,1]
	v_exp_f32_e32 v116, v116
	v_exp_f32_e32 v117, v117
	v_exp_f32_e32 v118, v118
	v_exp_f32_e32 v119, v119
	v_exp_f32_e32 v112, v112
	v_exp_f32_e32 v113, v113
	v_exp_f32_e32 v114, v114
	v_exp_f32_e32 v115, v115
	v_pk_fma_f32 v[116:117], v[116:117], v[154:155], v[154:155] op_sel_hi:[1,0,0]
	v_pk_fma_f32 v[118:119], v[118:119], v[154:155], v[154:155] op_sel_hi:[1,0,0]
	v_pk_fma_f32 v[112:113], v[112:113], v[154:155], v[154:155] op_sel_hi:[1,0,0]
	v_pk_fma_f32 v[114:115], v[114:115], v[154:155], v[154:155] op_sel_hi:[1,0,0]
	v_rcp_f32_e32 v116, v116
	v_rcp_f32_e32 v117, v117
	v_rcp_f32_e32 v118, v118
	v_rcp_f32_e32 v119, v119
	v_rcp_f32_e32 v112, v112
	v_rcp_f32_e32 v113, v113
	v_rcp_f32_e32 v114, v114
	v_rcp_f32_e32 v115, v115
	v_pk_mul_f32 v[124:125], v[124:125], v[116:117]
	v_pk_mul_f32 v[126:127], v[126:127], v[118:119]
	v_pk_mul_f32 v[120:121], v[120:121], v[112:113]
	v_pk_mul_f32 v[122:123], v[122:123], v[114:115]
	v_cvt_pk_bf16_f32 v208, v124, v125
	v_cvt_pk_bf16_f32 v209, v126, v127
	v_cvt_pk_bf16_f32 v210, v120, v121
	v_cvt_pk_bf16_f32 v211, v122, v123
	v_lshl_add_u64 v[176:177], s[68:69], 0, v[130:131]
	global_store_dwordx4 v[176:177], v[208:211], off sc1
	v_pk_mul_f32 v[108:109], v[108:109], v[162:163] op_sel:[0,1] op_sel_hi:[1,1]
	v_pk_mul_f32 v[110:111], v[110:111], v[162:163] op_sel:[0,1] op_sel_hi:[1,1]
	v_pk_mul_f32 v[100:101], v[100:101], v[162:163] op_sel:[0,1] op_sel_hi:[1,1]
	v_pk_mul_f32 v[102:103], v[102:103], v[162:163] op_sel:[0,1] op_sel_hi:[1,1]
	v_exp_f32_e32 v108, v108
	v_exp_f32_e32 v109, v109
	v_exp_f32_e32 v110, v110
	v_exp_f32_e32 v111, v111
	v_exp_f32_e32 v100, v100
	v_exp_f32_e32 v101, v101
	v_exp_f32_e32 v102, v102
	v_exp_f32_e32 v103, v103
	v_pk_fma_f32 v[108:109], v[108:109], v[162:163], v[162:163] op_sel_hi:[1,0,0]
	v_pk_fma_f32 v[110:111], v[110:111], v[162:163], v[162:163] op_sel_hi:[1,0,0]
	v_pk_fma_f32 v[100:101], v[100:101], v[162:163], v[162:163] op_sel_hi:[1,0,0]
	v_pk_fma_f32 v[102:103], v[102:103], v[162:163], v[162:163] op_sel_hi:[1,0,0]
	v_rcp_f32_e32 v108, v108
	v_rcp_f32_e32 v109, v109
	v_rcp_f32_e32 v110, v110
	v_rcp_f32_e32 v111, v111
	v_rcp_f32_e32 v100, v100
	v_rcp_f32_e32 v101, v101
	v_rcp_f32_e32 v102, v102
; __device__ __forceinline__ unsigned cvt_pk_bf16(float lo, float hi) { unsigned r; asm volatile("v_cvt_pk_bf16_f32 %0, %1, %2" : "=v"(r) : "v"(lo), "v"(hi)); return r; }
;     __device__ __forceinline__ void operator()(f32x4 (&acc)[2][2][4][2], const Unit& u, int wr, int wc, int fr, int fq) const {
;     ...
;             for (int m = 0; m < 4; ++m) { const float ms = sq[ai][m] * (1.0f / 1024.0f) + 1e-6f, nrl = -__builtin_amdgcn_rsqf(ms) * LOG2E;
;                 float o[8];
; #pragma unroll
;                 for (int n = 0; n < 2; ++n)
; #pragma unroll
;                     for (int e = 0; e < 4; ++e) { const float a = acc[ai][0][m][n][e], bb = acc[ai][1][m][n][e];
;                         o[4 * n + e] = (a * bb) * __builtin_amdgcn_rcpf(__builtin_fmaf(__builtin_amdgcn_exp2f(a * nrl), ms, ms)); }
;                 u32x4 w; w.x = cvt_pk_bf16(o[0], o[1]); w.y = cvt_pk_bf16(o[2], o[3]); w.z = cvt_pk_bf16(o[4], o[5]); w.w = cvt_pk_bf16(o[6], o[7]);
;                 *(u32x4*)((char*)Ob + ai * HTB + lds_byte(wr * 64 + m * 16 + fr, (col0 & 63))) = w; }
	v_rcp_f32_e32 v103, v103
	v_pk_mul_f32 v[104:105], v[104:105], v[108:109]
	v_pk_mul_f32 v[106:107], v[106:107], v[110:111]
	v_pk_mul_f32 v[96:97], v[96:97], v[100:101]
	v_pk_mul_f32 v[98:99], v[98:99], v[102:103]
	v_cvt_pk_bf16_f32 v212, v104, v105
	v_cvt_pk_bf16_f32 v213, v106, v107
	v_cvt_pk_bf16_f32 v214, v96, v97
	v_cvt_pk_bf16_f32 v215, v98, v99
	v_lshl_add_u64 v[176:177], s[68:69], 0, v[132:133]
	global_store_dwordx4 v[176:177], v[212:215], off sc1
	v_pk_mul_f32 v[92:93], v[92:93], v[164:165] op_sel:[0,1] op_sel_hi:[1,1]
	v_pk_mul_f32 v[94:95], v[94:95], v[164:165] op_sel:[0,1] op_sel_hi:[1,1]
	v_pk_mul_f32 v[84:85], v[84:85], v[164:165] op_sel:[0,1] op_sel_hi:[1,1]
	v_pk_mul_f32 v[86:87], v[86:87], v[164:165] op_sel:[0,1] op_sel_hi:[1,1]
	v_exp_f32_e32 v92, v92
	v_exp_f32_e32 v93, v93
	v_exp_f32_e32 v94, v94
	v_exp_f32_e32 v95, v95
	v_exp_f32_e32 v84, v84
	v_exp_f32_e32 v85, v85
	v_exp_f32_e32 v86, v86
	v_exp_f32_e32 v87, v87
	v_pk_fma_f32 v[92:93], v[92:93], v[164:165], v[164:165] op_sel_hi:[1,0,0]
	v_pk_fma_f32 v[94:95], v[94:95], v[164:165], v[164:165] op_sel_hi:[1,0,0]
	v_pk_fma_f32 v[84:85], v[84:85], v[164:165], v[164:165] op_sel_hi:[1,0,0]
	v_pk_fma_f32 v[86:87], v[86:87], v[164:165], v[164:165] op_sel_hi:[1,0,0]
	v_rcp_f32_e32 v92, v92
	v_rcp_f32_e32 v93, v93
	v_rcp_f32_e32 v94, v94
	v_rcp_f32_e32 v95, v95
	v_rcp_f32_e32 v84, v84
	v_rcp_f32_e32 v85, v85
	v_rcp_f32_e32 v86, v86
	v_rcp_f32_e32 v87, v87
	v_pk_mul_f32 v[88:89], v[88:89], v[92:93]
	v_pk_mul_f32 v[90:91], v[90:91], v[94:95]
	v_pk_mul_f32 v[80:81], v[80:81], v[84:85]
	v_pk_mul_f32 v[82:83], v[82:83], v[86:87]
	v_cvt_pk_bf16_f32 v208, v88, v89
	v_cvt_pk_bf16_f32 v209, v90, v91
	v_cvt_pk_bf16_f32 v210, v80, v81
	v_cvt_pk_bf16_f32 v211, v82, v83
	v_lshl_add_u64 v[176:177], s[68:69], 0, v[134:135]
	global_store_dwordx4 v[176:177], v[208:211], off sc1
	v_pk_mul_f32 v[76:77], v[76:77], v[166:167] op_sel:[0,1] op_sel_hi:[1,1]
	v_pk_mul_f32 v[78:79], v[78:79], v[166:167] op_sel:[0,1] op_sel_hi:[1,1]
	v_pk_mul_f32 v[68:69], v[68:69], v[166:167] op_sel:[0,1] op_sel_hi:[1,1]
	v_pk_mul_f32 v[70:71], v[70:71], v[166:167] op_sel:[0,1] op_sel_hi:[1,1]
	v_exp_f32_e32 v76, v76
	v_exp_f32_e32 v77, v77
	v_exp_f32_e32 v78, v78
	v_exp_f32_e32 v79, v79
	v_exp_f32_e32 v68, v68
	v_exp_f32_e32 v69, v69
	v_exp_f32_e32 v70, v70
	v_exp_f32_e32 v71, v71
	v_pk_fma_f32 v[76:77], v[76:77], v[166:167], v[166:167] op_sel_hi:[1,0,0]
	v_pk_fma_f32 v[78:79], v[78:79], v[166:167], v[166:167] op_sel_hi:[1,0,0]
	v_pk_fma_f32 v[68:69], v[68:69], v[166:167], v[166:167] op_sel_hi:[1,0,0]
	v_pk_fma_f32 v[70:71], v[70:71], v[166:167], v[166:167] op_sel_hi:[1,0,0]
	v_rcp_f32_e32 v76, v76
	v_rcp_f32_e32 v77, v77
	v_rcp_f32_e32 v78, v78
	v_rcp_f32_e32 v79, v79
	v_rcp_f32_e32 v68, v68
	v_rcp_f32_e32 v69, v69
	v_rcp_f32_e32 v70, v70
	v_rcp_f32_e32 v71, v71
	v_pk_mul_f32 v[72:73], v[72:73], v[76:77]
	v_pk_mul_f32 v[74:75], v[74:75], v[78:79]
	v_pk_mul_f32 v[64:65], v[64:65], v[68:69]
	v_pk_mul_f32 v[66:67], v[66:67], v[70:71]
	v_cvt_pk_bf16_f32 v212, v72, v73
	v_cvt_pk_bf16_f32 v213, v74, v75
	v_cvt_pk_bf16_f32 v214, v64, v65
	v_cvt_pk_bf16_f32 v215, v66, v67
	v_lshl_add_u64 v[176:177], s[68:69], 0, v[136:137]
	global_store_dwordx4 v[176:177], v[212:215], off sc1
	s_add_u32 s68, s68, 0x4000
	s_addc_u32 s69, s69, 0
	v_pk_mul_f32 v[60:61], v[60:61], v[168:169] op_sel:[0,1] op_sel_hi:[1,1]
	v_pk_mul_f32 v[62:63], v[62:63], v[168:169] op_sel:[0,1] op_sel_hi:[1,1]
	v_pk_mul_f32 v[52:53], v[52:53], v[168:169] op_sel:[0,1] op_sel_hi:[1,1]
	v_pk_mul_f32 v[54:55], v[54:55], v[168:169] op_sel:[0,1] op_sel_hi:[1,1]
	v_exp_f32_e32 v60, v60
	v_exp_f32_e32 v61, v61
	v_exp_f32_e32 v62, v62
	v_exp_f32_e32 v63, v63
	v_exp_f32_e32 v52, v52
	v_exp_f32_e32 v53, v53
	v_exp_f32_e32 v54, v54
	v_exp_f32_e32 v55, v55
	v_pk_fma_f32 v[60:61], v[60:61], v[168:169], v[168:169] op_sel_hi:[1,0,0]
	v_pk_fma_f32 v[62:63], v[62:63], v[168:169], v[168:169] op_sel_hi:[1,0,0]
	v_pk_fma_f32 v[52:53], v[52:53], v[168:169], v[168:169] op_sel_hi:[1,0,0]
	v_pk_fma_f32 v[54:55], v[54:55], v[168:169], v[168:169] op_sel_hi:[1,0,0]
	v_rcp_f32_e32 v60, v60
	v_rcp_f32_e32 v61, v61
	v_rcp_f32_e32 v62, v62
	v_rcp_f32_e32 v63, v63
	v_rcp_f32_e32 v52, v52
	v_rcp_f32_e32 v53, v53
	v_rcp_f32_e32 v54, v54
	v_rcp_f32_e32 v55, v55
	v_pk_mul_f32 v[56:57], v[56:57], v[60:61]
	v_pk_mul_f32 v[58:59], v[58:59], v[62:63]
	v_pk_mul_f32 v[48:49], v[48:49], v[52:53]
	v_pk_mul_f32 v[50:51], v[50:51], v[54:55]
	v_cvt_pk_bf16_f32 v208, v56, v57
; __device__ __forceinline__ unsigned cvt_pk_bf16(float lo, float hi) { unsigned r; asm volatile("v_cvt_pk_bf16_f32 %0, %1, %2" : "=v"(r) : "v"(lo), "v"(hi)); return r; }
;     __device__ __forceinline__ void operator()(f32x4 (&acc)[2][2][4][2], const Unit& u, int wr, int wc, int fr, int fq) const {
;     ...
;             for (int m = 0; m < 4; ++m) { const float ms = sq[ai][m] * (1.0f / 1024.0f) + 1e-6f, nrl = -__builtin_amdgcn_rsqf(ms) * LOG2E;
;                 float o[8];
; #pragma unroll
;                 for (int n = 0; n < 2; ++n)
; #pragma unroll
;                     for (int e = 0; e < 4; ++e) { const float a = acc[ai][0][m][n][e], bb = acc[ai][1][m][n][e];
;                         o[4 * n + e] = (a * bb) * __builtin_amdgcn_rcpf(__builtin_fmaf(__builtin_amdgcn_exp2f(a * nrl), ms, ms)); }
;                 u32x4 w; w.x = cvt_pk_bf16(o[0], o[1]); w.y = cvt_pk_bf16(o[2], o[3]); w.z = cvt_pk_bf16(o[4], o[5]); w.w = cvt_pk_bf16(o[6], o[7]);
;                 *(u32x4*)((char*)Ob + ai * HTB + lds_byte(wr * 64 + m * 16 + fr, (col0 & 63))) = w; }
	v_cvt_pk_bf16_f32 v209, v58, v59
	v_cvt_pk_bf16_f32 v210, v48, v49
	v_cvt_pk_bf16_f32 v211, v50, v51
	v_lshl_add_u64 v[176:177], s[68:69], 0, v[130:131]
	global_store_dwordx4 v[176:177], v[208:211], off sc1
	v_pk_mul_f32 v[44:45], v[44:45], v[170:171] op_sel:[0,1] op_sel_hi:[1,1]
	v_pk_mul_f32 v[46:47], v[46:47], v[170:171] op_sel:[0,1] op_sel_hi:[1,1]
	v_pk_mul_f32 v[36:37], v[36:37], v[170:171] op_sel:[0,1] op_sel_hi:[1,1]
	v_pk_mul_f32 v[38:39], v[38:39], v[170:171] op_sel:[0,1] op_sel_hi:[1,1]
	v_exp_f32_e32 v44, v44
	v_exp_f32_e32 v45, v45
	v_exp_f32_e32 v46, v46
	v_exp_f32_e32 v47, v47
	v_exp_f32_e32 v36, v36
	v_exp_f32_e32 v37, v37
	v_exp_f32_e32 v38, v38
	v_exp_f32_e32 v39, v39
	v_pk_fma_f32 v[44:45], v[44:45], v[170:171], v[170:171] op_sel_hi:[1,0,0]
	v_pk_fma_f32 v[46:47], v[46:47], v[170:171], v[170:171] op_sel_hi:[1,0,0]
	v_pk_fma_f32 v[36:37], v[36:37], v[170:171], v[170:171] op_sel_hi:[1,0,0]
	v_pk_fma_f32 v[38:39], v[38:39], v[170:171], v[170:171] op_sel_hi:[1,0,0]
	v_rcp_f32_e32 v44, v44
	v_rcp_f32_e32 v45, v45
	v_rcp_f32_e32 v46, v46
	v_rcp_f32_e32 v47, v47
	v_rcp_f32_e32 v36, v36
	v_rcp_f32_e32 v37, v37
	v_rcp_f32_e32 v38, v38
	v_rcp_f32_e32 v39, v39
	v_pk_mul_f32 v[40:41], v[40:41], v[44:45]
	v_pk_mul_f32 v[42:43], v[42:43], v[46:47]
	v_pk_mul_f32 v[32:33], v[32:33], v[36:37]
	v_pk_mul_f32 v[34:35], v[34:35], v[38:39]
	v_cvt_pk_bf16_f32 v212, v40, v41
	v_cvt_pk_bf16_f32 v213, v42, v43
	v_cvt_pk_bf16_f32 v214, v32, v33
	v_cvt_pk_bf16_f32 v215, v34, v35
	v_lshl_add_u64 v[176:177], s[68:69], 0, v[132:133]
	global_store_dwordx4 v[176:177], v[212:215], off sc1
	v_pk_mul_f32 v[28:29], v[28:29], v[172:173] op_sel:[0,1] op_sel_hi:[1,1]
	v_pk_mul_f32 v[30:31], v[30:31], v[172:173] op_sel:[0,1] op_sel_hi:[1,1]
	v_pk_mul_f32 v[20:21], v[20:21], v[172:173] op_sel:[0,1] op_sel_hi:[1,1]
	v_pk_mul_f32 v[22:23], v[22:23], v[172:173] op_sel:[0,1] op_sel_hi:[1,1]
	v_exp_f32_e32 v28, v28
	v_exp_f32_e32 v29, v29
	v_exp_f32_e32 v30, v30
	v_exp_f32_e32 v31, v31
	v_exp_f32_e32 v20, v20
	v_exp_f32_e32 v21, v21
	v_exp_f32_e32 v22, v22
	v_exp_f32_e32 v23, v23
	v_pk_fma_f32 v[28:29], v[28:29], v[172:173], v[172:173] op_sel_hi:[1,0,0]
	v_pk_fma_f32 v[30:31], v[30:31], v[172:173], v[172:173] op_sel_hi:[1,0,0]
	v_pk_fma_f32 v[20:21], v[20:21], v[172:173], v[172:173] op_sel_hi:[1,0,0]
	v_pk_fma_f32 v[22:23], v[22:23], v[172:173], v[172:173] op_sel_hi:[1,0,0]
	v_rcp_f32_e32 v28, v28
	v_rcp_f32_e32 v29, v29
	v_rcp_f32_e32 v30, v30
	v_rcp_f32_e32 v31, v31
	v_rcp_f32_e32 v20, v20
	v_rcp_f32_e32 v21, v21
	v_rcp_f32_e32 v22, v22
	v_rcp_f32_e32 v23, v23
	v_pk_mul_f32 v[24:25], v[24:25], v[28:29]
	v_pk_mul_f32 v[26:27], v[26:27], v[30:31]
	v_pk_mul_f32 v[16:17], v[16:17], v[20:21]
	v_pk_mul_f32 v[18:19], v[18:19], v[22:23]
	v_cvt_pk_bf16_f32 v208, v24, v25
	v_cvt_pk_bf16_f32 v209, v26, v27
	v_cvt_pk_bf16_f32 v210, v16, v17
	v_cvt_pk_bf16_f32 v211, v18, v19
	v_lshl_add_u64 v[176:177], s[68:69], 0, v[134:135]
	global_store_dwordx4 v[176:177], v[208:211], off sc1
	v_pk_mul_f32 v[12:13], v[12:13], v[174:175] op_sel:[0,1] op_sel_hi:[1,1]
	v_pk_mul_f32 v[14:15], v[14:15], v[174:175] op_sel:[0,1] op_sel_hi:[1,1]
	v_pk_mul_f32 v[4:5], v[4:5], v[174:175] op_sel:[0,1] op_sel_hi:[1,1]
	v_pk_mul_f32 v[6:7], v[6:7], v[174:175] op_sel:[0,1] op_sel_hi:[1,1]
	v_exp_f32_e32 v12, v12
	v_exp_f32_e32 v13, v13
	v_exp_f32_e32 v14, v14
	v_exp_f32_e32 v15, v15
	v_exp_f32_e32 v4, v4
	v_exp_f32_e32 v5, v5
	v_exp_f32_e32 v6, v6
	v_exp_f32_e32 v7, v7
	v_pk_fma_f32 v[12:13], v[12:13], v[174:175], v[174:175] op_sel_hi:[1,0,0]
	v_pk_fma_f32 v[14:15], v[14:15], v[174:175], v[174:175] op_sel_hi:[1,0,0]
	v_pk_fma_f32 v[4:5], v[4:5], v[174:175], v[174:175] op_sel_hi:[1,0,0]
	v_pk_fma_f32 v[6:7], v[6:7], v[174:175], v[174:175] op_sel_hi:[1,0,0]
	v_rcp_f32_e32 v12, v12
	v_rcp_f32_e32 v13, v13
	v_rcp_f32_e32 v14, v14
	v_rcp_f32_e32 v15, v15
	v_rcp_f32_e32 v4, v4
	v_rcp_f32_e32 v5, v5
	v_rcp_f32_e32 v6, v6
	v_rcp_f32_e32 v7, v7
	v_pk_mul_f32 v[8:9], v[8:9], v[12:13]
	v_pk_mul_f32 v[10:11], v[10:11], v[14:15]
	v_pk_mul_f32 v[0:1], v[0:1], v[4:5]
	v_pk_mul_f32 v[2:3], v[2:3], v[6:7]
	v_cvt_pk_bf16_f32 v212, v8, v9
	v_cvt_pk_bf16_f32 v213, v10, v11
	v_cvt_pk_bf16_f32 v214, v0, v1
	v_cvt_pk_bf16_f32 v215, v2, v3
	v_lshl_add_u64 v[176:177], s[68:69], 0, v[136:137]
	global_store_dwordx4 v[176:177], v[212:215], off sc1
	s_andn2_b64 vcc, exec, s[2:3]
	s_mov_b64 s[2:3], -1
	s_cbranch_vccnz .LBB0_137
	s_andn2_b64 vcc, exec, s[52:53]
	s_cbranch_vccnz .LBB0_136
	s_barrier
	s_branch .LBB0_136

; __device__ __forceinline__ unsigned cvt_pk_bf16(float lo, float hi) { unsigned r; asm volatile("v_cvt_pk_bf16_f32 %0, %1, %2" : "=v"(r) : "v"(lo), "v"(hi)); return r; }
;     __device__ __forceinline__ void operator()(f32x4 (&acc)[2][2][4][2], const Unit& u, int wr, int wc, int fr, int fq) const {
;     ...
;             for (int m = 0; m < 4; ++m) sq[ai][m] = ssq[row0 + ai * HALF + m * 16];
; #pragma unroll
;         for (int ai = 0; ai < 2; ++ai)
; #pragma unroll
;             for (int m = 0; m < 4; ++m) { const float ms = sq[ai][m] * (1.0f / 1024.0f) + 1e-6f, nrl = -__builtin_amdgcn_rsqf(ms) * LOG2E;
;                 float o[8];
; #pragma unroll
;                 for (int n = 0; n < 2; ++n)
; #pragma unroll
;                     for (int e = 0; e < 4; ++e) { const float a = acc[ai][0][m][n][e], bb = acc[ai][1][m][n][e];
;                         o[4 * n + e] = (a * bb) * __builtin_amdgcn_rcpf(__builtin_fmaf(__builtin_amdgcn_exp2f(a * nrl), ms, ms)); }
;                 u32x4 w; w.x = cvt_pk_bf16(o[0], o[1]); w.y = cvt_pk_bf16(o[2], o[3]); w.z = cvt_pk_bf16(o[4], o[5]); w.w = cvt_pk_bf16(o[6], o[7]);
;                 *(u32x4*)((char*)Ob + ai * HTB + lds_byte(wr * 64 + m * 16 + fr, (col0 & 63))) = w; }
.LBB0_841:
	v_lshl_add_u32 v148, s60, 8, v140
	v_ashrrev_i32_e32 v149, 31, v148
	v_lshl_add_u64 v[148:149], v[148:149], 2, s[0:1]
	global_load_dword v147, v[148:149], off
	global_load_dword v150, v[148:149], off offset:64
	global_load_dword v154, v[148:149], off offset:128
	global_load_dword v155, v[148:149], off offset:192
	global_load_dword v156, v[148:149], off offset:512
	global_load_dword v157, v[148:149], off offset:576
	global_load_dword v158, v[148:149], off offset:640
	global_load_dword v176, v[148:149], off offset:704
	s_lshl_b32 s53, s61, 7
	s_or_b32 s53, s53, s71
	s_mul_i32 s55, s60, 44
	s_ashr_i32 s53, s53, 6
	s_add_i32 s60, s53, s55
	s_ashr_i32 s61, s60, 31
	s_lshl_b64 s[60:61], s[60:61], 15
	s_add_u32 s60, s28, s60
	s_addc_u32 s61, s29, s61
	v_pk_mul_f32 v[124:125], v[116:117], v[124:125]
	v_pk_mul_f32 v[126:127], v[118:119], v[126:127]
	v_pk_mul_f32 v[120:121], v[112:113], v[120:121]
	v_pk_mul_f32 v[122:123], v[114:115], v[122:123]
	v_pk_mul_f32 v[104:105], v[108:109], v[104:105]
	v_pk_mul_f32 v[106:107], v[110:111], v[106:107]
	v_pk_mul_f32 v[96:97], v[100:101], v[96:97]
	v_pk_mul_f32 v[98:99], v[102:103], v[98:99]
	v_pk_mul_f32 v[88:89], v[92:93], v[88:89]
	v_pk_mul_f32 v[90:91], v[94:95], v[90:91]
	v_pk_mul_f32 v[80:81], v[84:85], v[80:81]
	v_pk_mul_f32 v[82:83], v[86:87], v[82:83]
	v_pk_mul_f32 v[72:73], v[76:77], v[72:73]
	v_pk_mul_f32 v[74:75], v[78:79], v[74:75]
	v_pk_mul_f32 v[64:65], v[68:69], v[64:65]
	v_pk_mul_f32 v[66:67], v[70:71], v[66:67]
	v_pk_mul_f32 v[56:57], v[60:61], v[56:57]
	v_pk_mul_f32 v[58:59], v[62:63], v[58:59]
	v_pk_mul_f32 v[48:49], v[52:53], v[48:49]
	v_pk_mul_f32 v[50:51], v[54:55], v[50:51]
	v_pk_mul_f32 v[40:41], v[44:45], v[40:41]
	v_pk_mul_f32 v[42:43], v[46:47], v[42:43]
	v_pk_mul_f32 v[32:33], v[36:37], v[32:33]
	v_pk_mul_f32 v[34:35], v[38:39], v[34:35]
	v_pk_mul_f32 v[24:25], v[28:29], v[24:25]
	v_pk_mul_f32 v[26:27], v[30:31], v[26:27]
	v_pk_mul_f32 v[16:17], v[20:21], v[16:17]
	v_pk_mul_f32 v[18:19], v[22:23], v[18:19]
	v_pk_mul_f32 v[8:9], v[12:13], v[8:9]
	v_pk_mul_f32 v[10:11], v[14:15], v[10:11]
	v_pk_mul_f32 v[0:1], v[4:5], v[0:1]
	v_pk_mul_f32 v[2:3], v[6:7], v[2:3]
	v_readlane_b32 s99, v246, 6
	s_nop 1
	s_cmp_lt_u32 s99, 4
	s_cbranch_scc0 .Lnoal_6
	s_barrier
.Lnoal_6:
	s_waitcnt vmcnt(0)
	v_fmamk_f32 v152, v147, 0x3a800000, v146
	v_fmamk_f32 v160, v150, 0x3a800000, v146
	v_fmamk_f32 v162, v154, 0x3a800000, v146
	v_fmamk_f32 v164, v155, 0x3a800000, v146
	v_fmamk_f32 v166, v156, 0x3a800000, v146
	v_fmamk_f32 v168, v157, 0x3a800000, v146
	v_fmamk_f32 v170, v158, 0x3a800000, v146
	v_fmamk_f32 v172, v176, 0x3a800000, v146
	v_rsq_f32_e32 v153, v152
	v_rsq_f32_e32 v161, v160
	v_rsq_f32_e32 v163, v162
	v_rsq_f32_e32 v165, v164
	v_rsq_f32_e32 v167, v166
	v_rsq_f32_e32 v169, v168
	v_rsq_f32_e32 v171, v170
	v_rsq_f32_e32 v173, v172
	v_mul_f32_e32 v153, 0xbfb8aa3b, v153
	v_mul_f32_e32 v161, 0xbfb8aa3b, v161
	v_mul_f32_e32 v163, 0xbfb8aa3b, v163
	v_mul_f32_e32 v165, 0xbfb8aa3b, v165
	v_mul_f32_e32 v167, 0xbfb8aa3b, v167
	v_mul_f32_e32 v169, 0xbfb8aa3b, v169
	v_mul_f32_e32 v171, 0xbfb8aa3b, v171
	v_mul_f32_e32 v173, 0xbfb8aa3b, v173
	v_pk_mul_f32 v[116:117], v[116:117], v[152:153] op_sel:[0,1] op_sel_hi:[1,1]
	v_pk_mul_f32 v[118:119], v[118:119], v[152:153] op_sel:[0,1] op_sel_hi:[1,1]
	v_pk_mul_f32 v[112:113], v[112:113], v[152:153] op_sel:[0,1] op_sel_hi:[1,1]
	v_pk_mul_f32 v[114:115], v[114:115], v[152:153] op_sel:[0,1] op_sel_hi:[1,1]
	v_exp_f32_e32 v116, v116
	v_exp_f32_e32 v117, v117
	v_exp_f32_e32 v118, v118
	v_exp_f32_e32 v119, v119
	v_exp_f32_e32 v112, v112
	v_exp_f32_e32 v113, v113
	v_exp_f32_e32 v114, v114
	v_exp_f32_e32 v115, v115
	v_pk_fma_f32 v[116:117], v[116:117], v[152:153], v[152:153] op_sel_hi:[1,0,0]
	v_pk_fma_f32 v[118:119], v[118:119], v[152:153], v[152:153] op_sel_hi:[1,0,0]
	v_pk_fma_f32 v[112:113], v[112:113], v[152:153], v[152:153] op_sel_hi:[1,0,0]
	v_pk_fma_f32 v[114:115], v[114:115], v[152:153], v[152:153] op_sel_hi:[1,0,0]
	v_rcp_f32_e32 v116, v116
	v_rcp_f32_e32 v117, v117
	v_rcp_f32_e32 v118, v118
	v_rcp_f32_e32 v119, v119
	v_rcp_f32_e32 v112, v112
	v_rcp_f32_e32 v113, v113
	v_rcp_f32_e32 v114, v114
	v_rcp_f32_e32 v115, v115
	v_pk_mul_f32 v[124:125], v[124:125], v[116:117]
	v_pk_mul_f32 v[126:127], v[126:127], v[118:119]
	v_pk_mul_f32 v[120:121], v[120:121], v[112:113]
	v_pk_mul_f32 v[122:123], v[122:123], v[114:115]
	v_cvt_pk_bf16_f32 v208, v124, v125
	v_cvt_pk_bf16_f32 v209, v126, v127
	v_cvt_pk_bf16_f32 v210, v120, v121
	v_cvt_pk_bf16_f32 v211, v122, v123
	v_lshl_add_u64 v[174:175], s[60:61], 0, v[128:129]
	global_store_dwordx4 v[174:175], v[208:211], off sc1
	v_pk_mul_f32 v[108:109], v[108:109], v[160:161] op_sel:[0,1] op_sel_hi:[1,1]
	v_pk_mul_f32 v[110:111], v[110:111], v[160:161] op_sel:[0,1] op_sel_hi:[1,1]
	v_pk_mul_f32 v[100:101], v[100:101], v[160:161] op_sel:[0,1] op_sel_hi:[1,1]
	v_pk_mul_f32 v[102:103], v[102:103], v[160:161] op_sel:[0,1] op_sel_hi:[1,1]
	v_exp_f32_e32 v108, v108
	v_exp_f32_e32 v109, v109
	v_exp_f32_e32 v110, v110
	v_exp_f32_e32 v111, v111
	v_exp_f32_e32 v100, v100
	v_exp_f32_e32 v101, v101
	v_exp_f32_e32 v102, v102
	v_exp_f32_e32 v103, v103
	v_pk_fma_f32 v[108:109], v[108:109], v[160:161], v[160:161] op_sel_hi:[1,0,0]
	v_pk_fma_f32 v[110:111], v[110:111], v[160:161], v[160:161] op_sel_hi:[1,0,0]
	v_pk_fma_f32 v[100:101], v[100:101], v[160:161], v[160:161] op_sel_hi:[1,0,0]
	v_pk_fma_f32 v[102:103], v[102:103], v[160:161], v[160:161] op_sel_hi:[1,0,0]
	v_rcp_f32_e32 v108, v108
	v_rcp_f32_e32 v109, v109
	v_rcp_f32_e32 v110, v110
	v_rcp_f32_e32 v111, v111
	v_rcp_f32_e32 v100, v100
	v_rcp_f32_e32 v101, v101
	v_rcp_f32_e32 v102, v102
; __device__ __forceinline__ unsigned cvt_pk_bf16(float lo, float hi) { unsigned r; asm volatile("v_cvt_pk_bf16_f32 %0, %1, %2" : "=v"(r) : "v"(lo), "v"(hi)); return r; }
;     __device__ __forceinline__ void operator()(f32x4 (&acc)[2][2][4][2], const Unit& u, int wr, int wc, int fr, int fq) const {
;     ...
;             for (int m = 0; m < 4; ++m) { const float ms = sq[ai][m] * (1.0f / 1024.0f) + 1e-6f, nrl = -__builtin_amdgcn_rsqf(ms) * LOG2E;
;                 float o[8];
; #pragma unroll
;                 for (int n = 0; n < 2; ++n)
; #pragma unroll
;                     for (int e = 0; e < 4; ++e) { const float a = acc[ai][0][m][n][e], bb = acc[ai][1][m][n][e];
;                         o[4 * n + e] = (a * bb) * __builtin_amdgcn_rcpf(__builtin_fmaf(__builtin_amdgcn_exp2f(a * nrl), ms, ms)); }
;                 u32x4 w; w.x = cvt_pk_bf16(o[0], o[1]); w.y = cvt_pk_bf16(o[2], o[3]); w.z = cvt_pk_bf16(o[4], o[5]); w.w = cvt_pk_bf16(o[6], o[7]);
;                 *(u32x4*)((char*)Ob + ai * HTB + lds_byte(wr * 64 + m * 16 + fr, (col0 & 63))) = w; }
	v_rcp_f32_e32 v103, v103
	v_pk_mul_f32 v[104:105], v[104:105], v[108:109]
	v_pk_mul_f32 v[106:107], v[106:107], v[110:111]
	v_pk_mul_f32 v[96:97], v[96:97], v[100:101]
	v_pk_mul_f32 v[98:99], v[98:99], v[102:103]
	v_cvt_pk_bf16_f32 v212, v104, v105
	v_cvt_pk_bf16_f32 v213, v106, v107
	v_cvt_pk_bf16_f32 v214, v96, v97
	v_cvt_pk_bf16_f32 v215, v98, v99
	v_lshl_add_u64 v[174:175], s[60:61], 0, v[130:131]
	global_store_dwordx4 v[174:175], v[212:215], off sc1
	v_pk_mul_f32 v[92:93], v[92:93], v[162:163] op_sel:[0,1] op_sel_hi:[1,1]
	v_pk_mul_f32 v[94:95], v[94:95], v[162:163] op_sel:[0,1] op_sel_hi:[1,1]
	v_pk_mul_f32 v[84:85], v[84:85], v[162:163] op_sel:[0,1] op_sel_hi:[1,1]
	v_pk_mul_f32 v[86:87], v[86:87], v[162:163] op_sel:[0,1] op_sel_hi:[1,1]
	v_exp_f32_e32 v92, v92
	v_exp_f32_e32 v93, v93
	v_exp_f32_e32 v94, v94
	v_exp_f32_e32 v95, v95
	v_exp_f32_e32 v84, v84
	v_exp_f32_e32 v85, v85
	v_exp_f32_e32 v86, v86
	v_exp_f32_e32 v87, v87
	v_pk_fma_f32 v[92:93], v[92:93], v[162:163], v[162:163] op_sel_hi:[1,0,0]
	v_pk_fma_f32 v[94:95], v[94:95], v[162:163], v[162:163] op_sel_hi:[1,0,0]
	v_pk_fma_f32 v[84:85], v[84:85], v[162:163], v[162:163] op_sel_hi:[1,0,0]
	v_pk_fma_f32 v[86:87], v[86:87], v[162:163], v[162:163] op_sel_hi:[1,0,0]
	v_rcp_f32_e32 v92, v92
	v_rcp_f32_e32 v93, v93
	v_rcp_f32_e32 v94, v94
	v_rcp_f32_e32 v95, v95
	v_rcp_f32_e32 v84, v84
	v_rcp_f32_e32 v85, v85
	v_rcp_f32_e32 v86, v86
	v_rcp_f32_e32 v87, v87
	v_pk_mul_f32 v[88:89], v[88:89], v[92:93]
	v_pk_mul_f32 v[90:91], v[90:91], v[94:95]
	v_pk_mul_f32 v[80:81], v[80:81], v[84:85]
	v_pk_mul_f32 v[82:83], v[82:83], v[86:87]
	v_cvt_pk_bf16_f32 v208, v88, v89
	v_cvt_pk_bf16_f32 v209, v90, v91
	v_cvt_pk_bf16_f32 v210, v80, v81
	v_cvt_pk_bf16_f32 v211, v82, v83
	v_lshl_add_u64 v[174:175], s[60:61], 0, v[132:133]
	global_store_dwordx4 v[174:175], v[208:211], off sc1
	v_pk_mul_f32 v[76:77], v[76:77], v[164:165] op_sel:[0,1] op_sel_hi:[1,1]
	v_pk_mul_f32 v[78:79], v[78:79], v[164:165] op_sel:[0,1] op_sel_hi:[1,1]
	v_pk_mul_f32 v[68:69], v[68:69], v[164:165] op_sel:[0,1] op_sel_hi:[1,1]
	v_pk_mul_f32 v[70:71], v[70:71], v[164:165] op_sel:[0,1] op_sel_hi:[1,1]
	v_exp_f32_e32 v76, v76
	v_exp_f32_e32 v77, v77
	v_exp_f32_e32 v78, v78
	v_exp_f32_e32 v79, v79
	v_exp_f32_e32 v68, v68
	v_exp_f32_e32 v69, v69
	v_exp_f32_e32 v70, v70
	v_exp_f32_e32 v71, v71
	v_pk_fma_f32 v[76:77], v[76:77], v[164:165], v[164:165] op_sel_hi:[1,0,0]
	v_pk_fma_f32 v[78:79], v[78:79], v[164:165], v[164:165] op_sel_hi:[1,0,0]
	v_pk_fma_f32 v[68:69], v[68:69], v[164:165], v[164:165] op_sel_hi:[1,0,0]
	v_pk_fma_f32 v[70:71], v[70:71], v[164:165], v[164:165] op_sel_hi:[1,0,0]
	v_rcp_f32_e32 v76, v76
	v_rcp_f32_e32 v77, v77
	v_rcp_f32_e32 v78, v78
	v_rcp_f32_e32 v79, v79
	v_rcp_f32_e32 v68, v68
	v_rcp_f32_e32 v69, v69
	v_rcp_f32_e32 v70, v70
	v_rcp_f32_e32 v71, v71
	v_pk_mul_f32 v[72:73], v[72:73], v[76:77]
	v_pk_mul_f32 v[74:75], v[74:75], v[78:79]
	v_pk_mul_f32 v[64:65], v[64:65], v[68:69]
	v_pk_mul_f32 v[66:67], v[66:67], v[70:71]
	v_cvt_pk_bf16_f32 v212, v72, v73
	v_cvt_pk_bf16_f32 v213, v74, v75
	v_cvt_pk_bf16_f32 v214, v64, v65
	v_cvt_pk_bf16_f32 v215, v66, v67
	v_lshl_add_u64 v[174:175], s[60:61], 0, v[134:135]
	global_store_dwordx4 v[174:175], v[212:215], off sc1
	s_add_u32 s60, s60, 0x4000
	s_addc_u32 s61, s61, 0
	v_pk_mul_f32 v[60:61], v[60:61], v[166:167] op_sel:[0,1] op_sel_hi:[1,1]
	v_pk_mul_f32 v[62:63], v[62:63], v[166:167] op_sel:[0,1] op_sel_hi:[1,1]
	v_pk_mul_f32 v[52:53], v[52:53], v[166:167] op_sel:[0,1] op_sel_hi:[1,1]
	v_pk_mul_f32 v[54:55], v[54:55], v[166:167] op_sel:[0,1] op_sel_hi:[1,1]
	v_exp_f32_e32 v60, v60
	v_exp_f32_e32 v61, v61
	v_exp_f32_e32 v62, v62
	v_exp_f32_e32 v63, v63
	v_exp_f32_e32 v52, v52
	v_exp_f32_e32 v53, v53
	v_exp_f32_e32 v54, v54
	v_exp_f32_e32 v55, v55
	v_pk_fma_f32 v[60:61], v[60:61], v[166:167], v[166:167] op_sel_hi:[1,0,0]
	v_pk_fma_f32 v[62:63], v[62:63], v[166:167], v[166:167] op_sel_hi:[1,0,0]
	v_pk_fma_f32 v[52:53], v[52:53], v[166:167], v[166:167] op_sel_hi:[1,0,0]
	v_pk_fma_f32 v[54:55], v[54:55], v[166:167], v[166:167] op_sel_hi:[1,0,0]
	v_rcp_f32_e32 v60, v60
	v_rcp_f32_e32 v61, v61
	v_rcp_f32_e32 v62, v62
	v_rcp_f32_e32 v63, v63
	v_rcp_f32_e32 v52, v52
	v_rcp_f32_e32 v53, v53
	v_rcp_f32_e32 v54, v54
	v_rcp_f32_e32 v55, v55
	v_pk_mul_f32 v[56:57], v[56:57], v[60:61]
	v_pk_mul_f32 v[58:59], v[58:59], v[62:63]
	v_pk_mul_f32 v[48:49], v[48:49], v[52:53]
	v_pk_mul_f32 v[50:51], v[50:51], v[54:55]
	v_cvt_pk_bf16_f32 v208, v56, v57
; __device__ __forceinline__ unsigned cvt_pk_bf16(float lo, float hi) { unsigned r; asm volatile("v_cvt_pk_bf16_f32 %0, %1, %2" : "=v"(r) : "v"(lo), "v"(hi)); return r; }
;     __device__ __forceinline__ void operator()(f32x4 (&acc)[2][2][4][2], const Unit& u, int wr, int wc, int fr, int fq) const {
;     ...
;             for (int m = 0; m < 4; ++m) { const float ms = sq[ai][m] * (1.0f / 1024.0f) + 1e-6f, nrl = -__builtin_amdgcn_rsqf(ms) * LOG2E;
;                 float o[8];
; #pragma unroll
;                 for (int n = 0; n < 2; ++n)
; #pragma unroll
;                     for (int e = 0; e < 4; ++e) { const float a = acc[ai][0][m][n][e], bb = acc[ai][1][m][n][e];
;                         o[4 * n + e] = (a * bb) * __builtin_amdgcn_rcpf(__builtin_fmaf(__builtin_amdgcn_exp2f(a * nrl), ms, ms)); }
;                 u32x4 w; w.x = cvt_pk_bf16(o[0], o[1]); w.y = cvt_pk_bf16(o[2], o[3]); w.z = cvt_pk_bf16(o[4], o[5]); w.w = cvt_pk_bf16(o[6], o[7]);
;                 *(u32x4*)((char*)Ob + ai * HTB + lds_byte(wr * 64 + m * 16 + fr, (col0 & 63))) = w; }
	v_cvt_pk_bf16_f32 v209, v58, v59
	v_cvt_pk_bf16_f32 v210, v48, v49
	v_cvt_pk_bf16_f32 v211, v50, v51
	v_lshl_add_u64 v[174:175], s[60:61], 0, v[128:129]
	global_store_dwordx4 v[174:175], v[208:211], off sc1
	v_pk_mul_f32 v[44:45], v[44:45], v[168:169] op_sel:[0,1] op_sel_hi:[1,1]
	v_pk_mul_f32 v[46:47], v[46:47], v[168:169] op_sel:[0,1] op_sel_hi:[1,1]
	v_pk_mul_f32 v[36:37], v[36:37], v[168:169] op_sel:[0,1] op_sel_hi:[1,1]
	v_pk_mul_f32 v[38:39], v[38:39], v[168:169] op_sel:[0,1] op_sel_hi:[1,1]
	v_exp_f32_e32 v44, v44
	v_exp_f32_e32 v45, v45
	v_exp_f32_e32 v46, v46
	v_exp_f32_e32 v47, v47
	v_exp_f32_e32 v36, v36
	v_exp_f32_e32 v37, v37
	v_exp_f32_e32 v38, v38
	v_exp_f32_e32 v39, v39
	v_pk_fma_f32 v[44:45], v[44:45], v[168:169], v[168:169] op_sel_hi:[1,0,0]
	v_pk_fma_f32 v[46:47], v[46:47], v[168:169], v[168:169] op_sel_hi:[1,0,0]
	v_pk_fma_f32 v[36:37], v[36:37], v[168:169], v[168:169] op_sel_hi:[1,0,0]
	v_pk_fma_f32 v[38:39], v[38:39], v[168:169], v[168:169] op_sel_hi:[1,0,0]
	v_rcp_f32_e32 v44, v44
	v_rcp_f32_e32 v45, v45
	v_rcp_f32_e32 v46, v46
	v_rcp_f32_e32 v47, v47
	v_rcp_f32_e32 v36, v36
	v_rcp_f32_e32 v37, v37
	v_rcp_f32_e32 v38, v38
	v_rcp_f32_e32 v39, v39
	v_pk_mul_f32 v[40:41], v[40:41], v[44:45]
	v_pk_mul_f32 v[42:43], v[42:43], v[46:47]
	v_pk_mul_f32 v[32:33], v[32:33], v[36:37]
	v_pk_mul_f32 v[34:35], v[34:35], v[38:39]
	v_cvt_pk_bf16_f32 v212, v40, v41
	v_cvt_pk_bf16_f32 v213, v42, v43
	v_cvt_pk_bf16_f32 v214, v32, v33
	v_cvt_pk_bf16_f32 v215, v34, v35
	v_lshl_add_u64 v[174:175], s[60:61], 0, v[130:131]
	global_store_dwordx4 v[174:175], v[212:215], off sc1
	v_pk_mul_f32 v[28:29], v[28:29], v[170:171] op_sel:[0,1] op_sel_hi:[1,1]
	v_pk_mul_f32 v[30:31], v[30:31], v[170:171] op_sel:[0,1] op_sel_hi:[1,1]
	v_pk_mul_f32 v[20:21], v[20:21], v[170:171] op_sel:[0,1] op_sel_hi:[1,1]
	v_pk_mul_f32 v[22:23], v[22:23], v[170:171] op_sel:[0,1] op_sel_hi:[1,1]
	v_exp_f32_e32 v28, v28
	v_exp_f32_e32 v29, v29
	v_exp_f32_e32 v30, v30
	v_exp_f32_e32 v31, v31
	v_exp_f32_e32 v20, v20
	v_exp_f32_e32 v21, v21
	v_exp_f32_e32 v22, v22
	v_exp_f32_e32 v23, v23
	v_pk_fma_f32 v[28:29], v[28:29], v[170:171], v[170:171] op_sel_hi:[1,0,0]
	v_pk_fma_f32 v[30:31], v[30:31], v[170:171], v[170:171] op_sel_hi:[1,0,0]
	v_pk_fma_f32 v[20:21], v[20:21], v[170:171], v[170:171] op_sel_hi:[1,0,0]
	v_pk_fma_f32 v[22:23], v[22:23], v[170:171], v[170:171] op_sel_hi:[1,0,0]
	v_rcp_f32_e32 v28, v28
	v_rcp_f32_e32 v29, v29
	v_rcp_f32_e32 v30, v30
	v_rcp_f32_e32 v31, v31
	v_rcp_f32_e32 v20, v20
	v_rcp_f32_e32 v21, v21
	v_rcp_f32_e32 v22, v22
	v_rcp_f32_e32 v23, v23
	v_pk_mul_f32 v[24:25], v[24:25], v[28:29]
	v_pk_mul_f32 v[26:27], v[26:27], v[30:31]
	v_pk_mul_f32 v[16:17], v[16:17], v[20:21]
	v_pk_mul_f32 v[18:19], v[18:19], v[22:23]
	v_cvt_pk_bf16_f32 v208, v24, v25
	v_cvt_pk_bf16_f32 v209, v26, v27
	v_cvt_pk_bf16_f32 v210, v16, v17
	v_cvt_pk_bf16_f32 v211, v18, v19
	v_lshl_add_u64 v[174:175], s[60:61], 0, v[132:133]
	global_store_dwordx4 v[174:175], v[208:211], off sc1
	v_pk_mul_f32 v[12:13], v[12:13], v[172:173] op_sel:[0,1] op_sel_hi:[1,1]
	v_pk_mul_f32 v[14:15], v[14:15], v[172:173] op_sel:[0,1] op_sel_hi:[1,1]
	v_pk_mul_f32 v[4:5], v[4:5], v[172:173] op_sel:[0,1] op_sel_hi:[1,1]
	v_pk_mul_f32 v[6:7], v[6:7], v[172:173] op_sel:[0,1] op_sel_hi:[1,1]
	v_exp_f32_e32 v12, v12
	v_exp_f32_e32 v13, v13
	v_exp_f32_e32 v14, v14
	v_exp_f32_e32 v15, v15
	v_exp_f32_e32 v4, v4
	v_exp_f32_e32 v5, v5
	v_exp_f32_e32 v6, v6
	v_exp_f32_e32 v7, v7
	v_pk_fma_f32 v[12:13], v[12:13], v[172:173], v[172:173] op_sel_hi:[1,0,0]
	v_pk_fma_f32 v[14:15], v[14:15], v[172:173], v[172:173] op_sel_hi:[1,0,0]
	v_pk_fma_f32 v[4:5], v[4:5], v[172:173], v[172:173] op_sel_hi:[1,0,0]
	v_pk_fma_f32 v[6:7], v[6:7], v[172:173], v[172:173] op_sel_hi:[1,0,0]
	v_rcp_f32_e32 v12, v12
	v_rcp_f32_e32 v13, v13
	v_rcp_f32_e32 v14, v14
	v_rcp_f32_e32 v15, v15
	v_rcp_f32_e32 v4, v4
	v_rcp_f32_e32 v5, v5
	v_rcp_f32_e32 v6, v6
	v_rcp_f32_e32 v7, v7
	v_pk_mul_f32 v[8:9], v[8:9], v[12:13]
	v_pk_mul_f32 v[10:11], v[10:11], v[14:15]
	v_pk_mul_f32 v[0:1], v[0:1], v[4:5]
	v_pk_mul_f32 v[2:3], v[2:3], v[6:7]
	v_cvt_pk_bf16_f32 v212, v8, v9
	v_cvt_pk_bf16_f32 v213, v10, v11
	v_cvt_pk_bf16_f32 v214, v0, v1
	v_cvt_pk_bf16_f32 v215, v2, v3
	v_lshl_add_u64 v[174:175], s[60:61], 0, v[134:135]
	global_store_dwordx4 v[174:175], v[212:215], off sc1
	s_andn2_b64 vcc, exec, s[2:3]
	s_mov_b64 s[2:3], -1
	s_cbranch_vccnz .LBB0_834
	s_andn2_b64 vcc, exec, s[42:43]
	s_cbranch_vccnz .LBB0_833
	s_barrier
	s_branch .LBB0_833
